# hgrn_local prologue: 7 serialized load-wait-add steps of the chunk-0 forget-gate prefix sum issued as 7 loads in flight, added in the same order
# speedup vs baseline: 1.0301x; 1.0036x over previous
.LBB0_454:
	s_ashr_i32 s88, s61, 5
	s_ashr_i32 s89, s88, 31
	s_lshl_b32 s16, s61, 8
	s_lshl_b64 s[88:89], s[88:89], 11
	s_and_b32 s16, s16, 0x700
	s_or_b32 s88, s88, s16
	s_mul_i32 s16, s89, 0x1600
	s_mul_hi_u32 s33, s88, 0x1600
	s_add_i32 s33, s33, s16
	s_mul_i32 s16, s88, 0x1600
	s_add_u32 s90, s34, s16
	s_addc_u32 s33, s35, s33
	s_lshl_b32 s16, s61, 4
	s_and_b32 s92, s16, 0x180
	s_lshl_b32 s16, s92, 1
	s_add_u32 s90, s90, s16
	s_addc_u32 s91, s33, 0
	s_waitcnt vmcnt(10)
	v_mov_b32_e32 v129, v5
	v_mov_b32_e32 v115, v5
	v_lshl_add_u64 v[144:145], s[90:91], 0, v[128:129]
	s_waitcnt vmcnt(9)
	v_mov_b32_e32 v131, v5
	v_lshl_add_u64 v[142:143], s[90:91], 0, v[114:115]
	v_mov_b32_e32 v117, v5
	v_lshl_add_u64 v[14:15], v[144:145], 0, v[130:131]
	v_lshl_add_u64 v[12:13], v[142:143], 0, v[116:117]
	global_load_dwordx4 v[6:9], v[14:15], off offset:2048
	global_load_ushort v4, v[12:13], off offset:1024
	v_mov_b32_e32 v119, v5
	v_lshl_add_u64 v[10:11], v[142:143], 0, v[118:119]
	s_mov_b64 vcc, 0x1600
	v_lshl_add_u64 v[2:3], v[10:11], 0, vcc
	s_mov_b64 vcc, 0x2c00
	v_lshl_add_u64 v[16:17], v[10:11], 0, vcc
	v_mov_b32_e32 v121, v5
	v_lshl_add_u64 v[18:19], v[142:143], 0, v[120:121]
	v_mov_b32_e32 v123, v5
	v_lshl_add_u64 v[20:21], v[142:143], 0, v[122:123]
	v_mov_b32_e32 v125, v5
	v_lshl_add_u64 v[22:23], v[142:143], 0, v[124:125]
	v_mov_b32_e32 v127, v5
	v_lshl_add_u64 v[24:25], v[142:143], 0, v[126:127]
	v_lshl_add_u64 v[146:147], v[106:107], 0, s[16:17]
	s_movk_i32 s16, 0x2000
	global_load_ushort v41, v[10:11], off
	global_load_ushort v188, v[10:11], off offset:1024
	global_load_ushort v189, v[2:3], off offset:1024
	global_load_ushort v190, v[16:17], off offset:1024
	global_load_ushort v191, v[18:19], off offset:1024
	global_load_ushort v192, v[20:21], off offset:1024
	global_load_ushort v193, v[22:23], off offset:1024
	global_load_ushort v194, v[24:25], off offset:1024
	s_waitcnt vmcnt(8)
	v_lshlrev_b32_e32 v4, 16, v4
	v_add_f32_e32 v36, 0, v4
	s_waitcnt vmcnt(6)
	v_lshlrev_b32_e32 v4, 16, v188
	v_add_f32_e32 v40, v36, v4
	s_waitcnt vmcnt(5)
	v_lshlrev_b32_e32 v4, 16, v189
	v_add_f32_e32 v33, v40, v4
	s_waitcnt vmcnt(4)
	v_lshlrev_b32_e32 v4, 16, v190
	v_add_f32_e32 v32, v33, v4
	s_waitcnt vmcnt(3)
	v_lshlrev_b32_e32 v4, 16, v191
	v_add_f32_e32 v31, v32, v4
	s_waitcnt vmcnt(2)
	v_lshlrev_b32_e32 v4, 16, v192
	v_add_f32_e32 v30, v31, v4
	s_waitcnt vmcnt(1)
	v_lshlrev_b32_e32 v4, 16, v193
	v_add_f32_e32 v29, v30, v4
	s_waitcnt vmcnt(0)
	v_lshlrev_b32_e32 v4, 16, v194
	v_add_f32_e32 v27, v29, v4
	ds_bpermute_b32 v16, v91, v27
	ds_bpermute_b32 v34, v93, v27
	ds_bpermute_b32 v17, v95, v27
	ds_bpermute_b32 v35, v97, v27
	s_waitcnt lgkmcnt(3)
	v_cndmask_b32_e64 v4, v16, 0, s[4:5]
	s_waitcnt lgkmcnt(2)
	v_cndmask_b32_e64 v26, 0, v34, s[6:7]
	v_add_f32_e32 v4, v4, v26
	s_waitcnt lgkmcnt(1)
	v_cndmask_b32_e64 v26, 0, v17, s[8:9]
	v_add_f32_e32 v28, v4, v26
	s_waitcnt lgkmcnt(0)
	v_pk_add_f32 v[16:17], v[16:17], v[34:35]
	v_add_co_u32_e32 v34, vcc, s67, v10
	v_add_f32_e32 v26, v16, v17
	v_mul_f32_e32 v16, 0x3fb8aa3b, v28
	v_exp_f32_e32 v16, v16
	v_add_f32_e32 v17, v36, v28
	v_mul_f32_e32 v17, 0x3fb8aa3b, v17
	v_exp_f32_e32 v38, v17
	v_rcp_f32_e32 v16, v16
	v_addc_co_u32_e32 v35, vcc, 0, v11, vcc
	global_load_ushort v36, v[34:35], off offset:1536
	v_fma_f32 v17, -v16, v38, 1.0
	global_load_ushort v16, v[12:13], off
	v_add_co_u32_e32 v34, vcc, s16, v10
	v_rcp_f32_e32 v39, v38
	s_nop 0
	v_addc_co_u32_e32 v35, vcc, 0, v11, vcc
	global_load_ushort v35, v[34:35], off offset:3072
	s_nop 0
	global_load_ushort v37, v[18:19], off
	global_load_ushort v34, v[20:21], off
	s_nop 0
	global_load_ushort v23, v[22:23], off
	s_nop 0
	global_load_ushort v22, v[24:25], off
	v_mov_b32_e32 v19, s89
	v_mov_b32_e32 v25, s89
	v_or_b32_e32 v24, s88, v92
	v_lshlrev_b64 v[24:25], 10, v[24:25]
	v_lshl_add_u64 v[24:25], v[146:147], 0, v[24:25]
	v_mul_f32_e32 v4, 0x3fb8aa3b, v26
	v_exp_f32_e32 v4, v4
	s_waitcnt vmcnt(5)
	v_lshlrev_b32_e32 v16, 16, v16
	v_pk_mul_f32 v[16:17], v[38:39], v[16:17]
	s_waitcnt vmcnt(2)
	v_lshlrev_b32_e32 v34, 16, v34
	v_bfe_u32 v18, v16, 16, 1
	v_cvt_pk_bf16_f32 v38, v16, v17
	v_add3_u32 v16, v16, v18, s96
	v_or_b32_e32 v18, s88, v90
	v_lshlrev_b64 v[18:19], 10, v[18:19]
	v_lshl_add_u64 v[18:19], v[146:147], 0, v[18:19]
	ds_write_b16 v101, v38
	ds_write_b16_d16_hi v101, v38 offset:8832
	global_store_short_d16_hi v[18:19], v16, off
	v_add_f32_e32 v16, v40, v28
	v_mul_f32_e32 v16, 0x3fb8aa3b, v16
	v_exp_f32_e32 v20, v16
	v_lshlrev_b32_e32 v18, 16, v41
	v_or_b32_e32 v38, s88, v94
	s_waitcnt vmcnt(1)
	v_lshlrev_b32_e32 v22, 16, v22
	v_rcp_f32_e32 v21, v20
	v_fma_f32 v19, -v20, v39, 1.0
	v_mov_b32_e32 v39, s89
	v_lshlrev_b64 v[38:39], 10, v[38:39]
	v_pk_mul_f32 v[18:19], v[20:21], v[18:19]
	v_lshlrev_b32_e32 v20, 16, v36
	v_cvt_pk_bf16_f32 v16, v18, v19
	ds_write_b16 v105, v16
	ds_write_b16_d16_hi v105, v16 offset:8832
	v_bfe_u32 v16, v18, 16, 1
	v_add3_u32 v16, v18, v16, s96
	global_store_short_d16_hi v[24:25], v16, off
	v_add_f32_e32 v16, v33, v28
	v_mul_f32_e32 v16, 0x3fb8aa3b, v16
	v_exp_f32_e32 v24, v16
	v_lshl_add_u64 v[38:39], v[146:147], 0, v[38:39]
	v_or_b32_e32 v36, s88, v98
	v_rcp_f32_e32 v25, v24
	v_fma_f32 v21, -v24, v21, 1.0
	v_pk_mul_f32 v[20:21], v[24:25], v[20:21]
	s_nop 0
	v_cvt_pk_bf16_f32 v16, v20, v21
	ds_write_b16 v157, v16
	ds_write_b16_d16_hi v157, v16 offset:8832
	v_bfe_u32 v16, v20, 16, 1
	v_add3_u32 v16, v20, v16, s96
	global_store_short_d16_hi v[38:39], v16, off
	v_add_f32_e32 v16, v32, v28
	v_mul_f32_e32 v16, 0x3fb8aa3b, v16
	v_exp_f32_e32 v32, v16
	v_lshlrev_b32_e32 v24, 16, v35
	v_mov_b32_e32 v39, s89
	v_or_b32_e32 v38, s88, v96
	v_rcp_f32_e32 v33, v32
	v_fma_f32 v25, -v32, v25, 1.0
	v_lshlrev_b64 v[38:39], 10, v[38:39]
	v_lshl_add_u64 v[38:39], v[146:147], 0, v[38:39]
	v_pk_mul_f32 v[24:25], v[32:33], v[24:25]
	v_lshlrev_b32_e32 v32, 16, v37
	v_cvt_pk_bf16_f32 v16, v24, v25
	ds_write_b16 v159, v16
	ds_write_b16_d16_hi v159, v16 offset:8832
	v_bfe_u32 v16, v24, 16, 1
	v_add3_u32 v16, v24, v16, s96
	global_store_short_d16_hi v[38:39], v16, off
	v_add_f32_e32 v16, v31, v28
	v_mul_f32_e32 v16, 0x3fb8aa3b, v16
	v_exp_f32_e32 v38, v16
	v_mov_b32_e32 v37, s89
	v_lshlrev_b64 v[36:37], 10, v[36:37]
	v_lshl_add_u64 v[36:37], v[146:147], 0, v[36:37]
	v_rcp_f32_e32 v39, v38
	v_fma_f32 v33, -v38, v33, 1.0
	v_mov_b32_e32 v24, v19
	v_mov_b32_e32 v20, v17
	v_pk_mul_f32 v[32:33], v[38:39], v[32:33]
	v_or_b32_e32 v38, s88, v102
	v_cvt_pk_bf16_f32 v16, v32, v33
	ds_write_b16 v161, v16
	ds_write_b16_d16_hi v161, v16 offset:8832
	v_bfe_u32 v16, v32, 16, 1
	v_add3_u32 v16, v32, v16, s96
	global_store_short_d16_hi v[36:37], v16, off
	v_add_f32_e32 v16, v30, v28
	v_mul_f32_e32 v16, 0x3fb8aa3b, v16
	v_exp_f32_e32 v30, v16
	v_mov_b32_e32 v37, s89
	v_or_b32_e32 v36, s88, v100
	v_lshlrev_b64 v[36:37], 10, v[36:37]
	v_rcp_f32_e32 v31, v30
	v_fma_f32 v35, -v30, v39, 1.0
	v_lshl_add_u64 v[36:37], v[146:147], 0, v[36:37]
	v_mov_b32_e32 v39, s89
	v_pk_mul_f32 v[34:35], v[30:31], v[34:35]
	v_lshlrev_b32_e32 v30, 16, v23
	v_cvt_pk_bf16_f32 v16, v34, v35
	ds_write_b16 v163, v16
	ds_write_b16_d16_hi v163, v16 offset:8832
	v_bfe_u32 v16, v34, 16, 1
	v_add3_u32 v16, v34, v16, s96
	global_store_short_d16_hi v[36:37], v16, off
	v_add_f32_e32 v16, v29, v28
	v_mul_f32_e32 v16, 0x3fb8aa3b, v16
	v_exp_f32_e32 v36, v16
	v_lshlrev_b64 v[38:39], 10, v[38:39]
	v_lshl_add_u64 v[38:39], v[146:147], 0, v[38:39]
	v_pk_mul_f32 v[18:19], v[4:5], v[24:25] op_sel_hi:[0,1]
	v_rcp_f32_e32 v37, v36
	v_fma_f32 v31, -v36, v31, 1.0
	v_pk_mul_f32 v[30:31], v[36:37], v[30:31]
	s_nop 0
	v_cvt_pk_bf16_f32 v16, v30, v31
	ds_write_b16 v165, v16
	ds_write_b16_d16_hi v165, v16 offset:8832
	v_bfe_u32 v16, v30, 16, 1
	v_add3_u32 v16, v30, v16, s96
	global_store_short_d16_hi v[38:39], v16, off
	v_add_f32_e32 v16, v27, v28
	v_mul_f32_e32 v16, 0x3fb8aa3b, v16
	v_exp_f32_e32 v28, v16
	v_mov_b32_e32 v30, v33
	v_bfe_u32 v27, v19, 16, 1
	v_add3_u32 v27, v19, v27, s96
	v_rcp_f32_e32 v29, v28
	v_fma_f32 v23, -v28, v37, 1.0
	v_pk_mul_f32 v[22:23], v[28:29], v[22:23]
	s_nop 0
	v_cvt_pk_bf16_f32 v16, v22, v23
	ds_write_b16 v167, v16
	ds_write_b16_d16_hi v167, v16 offset:8832
	v_bfe_u32 v16, v22, 16, 1
	v_mov_b32_e32 v29, s89
	v_or_b32_e32 v28, s88, v104
	v_add3_u32 v16, v22, v16, s96
	v_lshlrev_b64 v[28:29], 10, v[28:29]
	v_mov_b32_e32 v22, v35
	v_lshl_add_u64 v[28:29], v[146:147], 0, v[28:29]
	v_pk_mul_f32 v[22:23], v[4:5], v[22:23] op_sel_hi:[0,1]
	global_store_short_d16_hi v[28:29], v16, off
	v_pk_mul_f32 v[16:17], v[4:5], v[20:21] op_sel_hi:[0,1]
	v_pk_mul_f32 v[20:21], v[4:5], v[30:31] op_sel_hi:[0,1]
	v_bfe_u32 v24, v23, 16, 1
	v_bfe_u32 v25, v22, 16, 1
	v_bfe_u32 v28, v18, 16, 1
	v_add3_u32 v28, v18, v28, s96
	v_add3_u32 v18, v22, v25, s96
	v_add3_u32 v19, v23, v24, s96
	v_bfe_u32 v22, v16, 16, 1
	v_bfe_u32 v23, v17, 16, 1
	v_bfe_u32 v24, v20, 16, 1
; #define LDS_BARRIER() do { asm volatile("s_waitcnt lgkmcnt(0)" ::: "memory"); __builtin_amdgcn_s_barrier(); asm volatile("" ::: "memory"); } while (0)
; #define HG_LOAD_RAW(ch) do { _Pragma("unroll") for (int j = 0; j < 8; ++j) { const size_t t_ = (size_t)((ch) * 32 + 8 * part + j); rq[j] = pq[t_ * PW]; rf[j] = pf[t_ * PW]; } \
;         rv = *(const v4u*)(pv + (size_t)((ch) * 32 + vt_t) * PW); } while (0)
; #define HG_LOAD_RAW(ch) do { _Pragma("unroll") for (int j = 0; j < 8; ++j) { const size_t t_ = (size_t)((ch) * 32 + 8 * part + j); rq[j] = pq[t_ * PW]; rf[j] = pf[t_ * PW]; } \
;         rv = *(const v4u*)(pv + (size_t)((ch) * 32 + vt_t) * PW); } while (0)
; __device__ __forceinline__ void hgrn_local_ws2(Frame& F, int item) {
;     ...
;     f32x4 S[2][8];
; #pragma unroll
;     for (int g = 0; g < 2; ++g)
; #pragma unroll
;         for (int i = 0; i < 8; ++i) S[g][i] = (f32x4){0.f, 0.f, 0.f, 0.f};
;     ...
;     HG_LOAD_RAW(0);
;     HG_ELEM(0);
;     HG_LOAD_RAW(1);
;     LDS_BARRIER();
	v_bfe_u32 v25, v21, 16, 1
	v_add3_u32 v21, v21, v25, s96
	v_add3_u32 v20, v20, v24, s96
	v_add3_u32 v17, v17, v23, s96
	v_add3_u32 v16, v16, v22, s96
	v_lshrrev_b32_e32 v16, 16, v16
	v_lshrrev_b32_e32 v17, 16, v17
	v_lshrrev_b32_e32 v20, 16, v20
	v_lshrrev_b32_e32 v21, 16, v21
	v_and_or_b32 v19, v19, s97, v21
	v_and_or_b32 v18, v18, s97, v20
	v_and_or_b32 v17, v27, s97, v17
	v_and_or_b32 v16, v28, s97, v16
	ds_write_b128 v169, v[16:19] offset:17664
	s_and_saveexec_b64 s[90:91], s[4:5]
	ds_write_b32 v174, v4 offset:39104
	s_or_b64 exec, exec, s[90:91]
	v_lshl_add_u64 v[16:17], v[12:13], 0, s[22:23]
	v_add_co_u32_e32 v12, vcc, s60, v12
	v_lshl_add_u64 v[18:19], v[10:11], 0, s[22:23]
	s_nop 0
	v_addc_co_u32_e32 v13, vcc, 0, v13, vcc
	v_add_co_u32_e32 v16, vcc, s60, v16
	v_lshl_add_u64 v[20:21], v[2:3], 0, s[22:23]
	s_nop 0
	v_addc_co_u32_e32 v17, vcc, 0, v17, vcc
	v_add_co_u32_e32 v10, vcc, s60, v10
	v_lshl_add_u64 v[22:23], v[142:143], 0, s[22:23]
	s_nop 0
	v_addc_co_u32_e32 v11, vcc, 0, v11, vcc
	v_add_co_u32_e32 v18, vcc, s60, v18
	v_mov_b32_e32 v133, v5
	s_nop 0
	v_addc_co_u32_e32 v19, vcc, 0, v19, vcc
	v_add_co_u32_e32 v2, vcc, s60, v2
	v_mov_b32_e32 v135, v5
	s_nop 0
	v_addc_co_u32_e32 v3, vcc, 0, v3, vcc
	v_add_co_u32_e32 v20, vcc, s60, v20
	v_lshl_add_u64 v[24:25], v[142:143], 0, v[132:133]
	s_nop 0
	v_addc_co_u32_e32 v21, vcc, 0, v21, vcc
	v_lshl_add_u64 v[28:29], v[22:23], 0, v[132:133]
	global_load_ushort v117, v[12:13], off
	global_load_ushort v119, v[16:17], off
	global_load_ushort v121, v[10:11], off
	global_load_ushort v123, v[18:19], off
	global_load_ushort v125, v[2:3], off
	global_load_ushort v127, v[20:21], off
	global_load_ushort v129, v[24:25], off
	global_load_ushort v131, v[28:29], off
	v_lshl_add_u64 v[2:3], v[142:143], 0, v[134:135]
	v_mov_b32_e32 v137, v5
	v_mov_b32_e32 v139, v5
	v_mov_b32_e32 v141, v5
	v_lshl_add_u64 v[10:11], v[22:23], 0, v[134:135]
	v_lshl_add_u64 v[12:13], v[142:143], 0, v[136:137]
	v_lshl_add_u64 v[16:17], v[22:23], 0, v[136:137]
	v_lshl_add_u64 v[18:19], v[142:143], 0, v[138:139]
	v_lshl_add_u64 v[20:21], v[22:23], 0, v[138:139]
	v_lshl_add_u64 v[24:25], v[142:143], 0, v[140:141]
	v_lshl_add_u64 v[22:23], v[22:23], 0, v[140:141]
	global_load_ushort v133, v[2:3], off
	global_load_ushort v135, v[10:11], off
	global_load_ushort v137, v[12:13], off
	global_load_ushort v139, v[16:17], off
	global_load_ushort v141, v[18:19], off
	global_load_ushort v187, v[20:21], off
	global_load_ushort v188, v[24:25], off
	global_load_ushort v189, v[22:23], off
	v_lshl_add_u64 v[14:15], v[14:15], 0, s[24:25]
	v_add_co_u32_e32 v2, vcc, 0x2c000, v14
	v_mov_b32_e32 v4, v5
	s_nop 0
	v_addc_co_u32_e32 v3, vcc, 0, v15, vcc
	global_load_dwordx4 v[70:73], v[2:3], off
	ds_write_b16 v173, v6 offset:27904
	ds_write_b16_d16_hi v173, v6 offset:27984
	ds_write_b16 v173, v7 offset:28064
	ds_write_b16_d16_hi v173, v7 offset:28144
	ds_write_b16 v173, v8 offset:28224
	ds_write_b16_d16_hi v173, v8 offset:28304
	ds_write_b16 v173, v9 offset:28384
	ds_write_b16_d16_hi v173, v9 offset:28464
	s_waitcnt lgkmcnt(0)
	s_barrier
	v_add_f32_e32 v115, 0, v26
	s_lshl_b32 s16, s92, 2
	v_mov_b32_e32 v2, v5
	v_mov_b32_e32 v3, v5
	v_mov_b64_e32 v[64:65], v[4:5]
	v_mov_b64_e32 v[68:69], v[4:5]
	v_mov_b64_e32 v[56:57], v[4:5]
	v_mov_b64_e32 v[60:61], v[4:5]
	v_mov_b64_e32 v[48:49], v[4:5]
	v_mov_b64_e32 v[52:53], v[4:5]
	v_mov_b64_e32 v[40:41], v[4:5]
	v_mov_b64_e32 v[44:45], v[4:5]
	v_mov_b64_e32 v[36:37], v[4:5]
	v_mov_b64_e32 v[32:33], v[4:5]
	v_mov_b64_e32 v[28:29], v[4:5]
	v_mov_b64_e32 v[24:25], v[4:5]
	v_mov_b64_e32 v[20:21], v[4:5]
	v_mov_b64_e32 v[16:17], v[4:5]
	v_mov_b64_e32 v[12:13], v[4:5]
	v_mov_b64_e32 v[8:9], v[4:5]
	s_mov_b32 s33, 0
	v_lshl_add_u64 v[148:149], v[110:111], 0, s[16:17]
	v_mov_b64_e32 v[62:63], v[2:3]
	v_mov_b64_e32 v[66:67], v[2:3]
	v_mov_b64_e32 v[54:55], v[2:3]
	v_mov_b64_e32 v[58:59], v[2:3]
	v_mov_b64_e32 v[46:47], v[2:3]
	v_mov_b64_e32 v[50:51], v[2:3]
	v_mov_b64_e32 v[38:39], v[2:3]
	v_mov_b64_e32 v[42:43], v[2:3]
	v_mov_b64_e32 v[34:35], v[2:3]
	v_mov_b64_e32 v[30:31], v[2:3]
	v_mov_b64_e32 v[26:27], v[2:3]
	v_mov_b64_e32 v[22:23], v[2:3]
	v_mov_b64_e32 v[18:19], v[2:3]
	v_mov_b64_e32 v[14:15], v[2:3]
	v_mov_b64_e32 v[10:11], v[2:3]
	v_mov_b64_e32 v[6:7], v[2:3]
	s_branch .LBB0_459
